# EpiResidNorm part 2 in all three residual phases (P4, P10, P13): column-half-1 gain loads issued with half 0's, no wait behind half-0 store acknowledgements
# baseline (speedup 1.0000x reference)
;     __device__ __forceinline__ void operator()(AccT& acc, const pg8::Unit& u, int wr, int wc, int fr_, int fq_) const {
;     ...
;         const float* sh = MODE == 0 ? shift + (size_t)bidx * NADA : nullptr;
; #pragma unroll
;         for (int bj = 0; bj < 2; ++bj) { const int col = u.pn * 256 + bj * 128 + wc * 32 + 8 * fq;
;             const f32x4 g0 = *(const f32x4*)(gvec + col), g1 = *(const f32x4*)(gvec + col + 4);
;             f32x4 a0 = g0, a1 = g1, b0 = {0.f, 0.f, 0.f, 0.f}, b1 = b0;
;             if (MODE == 0) { a0 = g0 * (*(const f32x4*)(sh + D + col) + 1.f); a1 = g1 * (*(const f32x4*)(sh + D + col + 4) + 1.f); b0 = *(const f32x4*)(sh + col); b1 = *(const f32x4*)(sh + col + 4); }
; #pragma unroll
;             for (int ai = 0; ai < 2; ++ai)
; #pragma unroll
;                 for (int m = 0; m < 4; ++m) { const int rl = ai * 128 + wr * 64 + m * 16 + fr; const size_t row = (size_t)u.pm * 256 + rl; const float rstd = sred[1024 + rl];
;                     const f32x4 y0 = acc[ai][bj][m][0] * rstd * a0 + b0, y1 = acc[ai][bj][m][1] * rstd * a1 + b1;
;                     if (MODE == 0) *(bf16x8*)(Hout + row * D + col) = pack8(y0[0], y0[1], y0[2], y0[3], y1[0], y1[1], y1[2], y1[3]);
;                     else { __builtin_nontemporal_store(y0, (f32x4*)(X + row * D + col)); __builtin_nontemporal_store(y1, (f32x4*)(X + row * D + col + 4)); }
;                     __builtin_amdgcn_sched_barrier(0); }
.LBB0_2349:
	s_or_b64 exec, exec, s[4:5]
	v_lshl_add_u64 v[156:157], s[16:17], 0, v[144:145]
	s_waitcnt lgkmcnt(0)
	s_barrier
	global_load_dwordx4 v[4:7], v[156:157], off
	global_load_dwordx4 v[0:3], v[156:157], off offset:16
	global_load_dwordx4 v[196:199], v[156:157], off offset:512
	global_load_dwordx4 v[200:203], v[156:157], off offset:528
	s_add_i32 s4, 0, 0x20000
	v_lshl_add_u32 v169, v146, 2, s4
	ds_read_b32 v172, v169 offset:4096
	v_ashrrev_i32_e32 v147, 31, v146
	v_lshlrev_b64 v[158:159], 20, v[158:159]
	v_lshl_add_u64 v[174:175], s[14:15], 0, v[158:159]
	v_lshlrev_b64 v[158:159], 12, v[146:147]
	v_lshl_add_u64 v[158:159], v[174:175], 0, v[158:159]
	s_waitcnt lgkmcnt(0)
	v_pk_mul_f32 v[126:127], v[126:127], v[172:173] op_sel_hi:[1,0]
	v_pk_mul_f32 v[124:125], v[124:125], v[172:173] op_sel_hi:[1,0]
	v_add_u32_e32 v170, 0x80, v146
	v_lshl_add_u64 v[158:159], v[158:159], 0, v[144:145]
	v_pk_mul_f32 v[176:177], v[122:123], v[172:173] op_sel_hi:[1,0]
	v_pk_mul_f32 v[172:173], v[120:121], v[172:173] op_sel_hi:[1,0]
	v_ashrrev_i32_e32 v171, 31, v170
	s_waitcnt vmcnt(3)
	v_pk_fma_f32 v[122:123], v[6:7], v[126:127], 0 op_sel_hi:[1,1,0]
	v_pk_fma_f32 v[120:121], v[4:5], v[124:125], 0 op_sel_hi:[1,1,0]
	s_waitcnt vmcnt(2)
	v_pk_fma_f32 v[126:127], v[2:3], v[176:177], 0 op_sel_hi:[1,1,0]
	v_pk_fma_f32 v[124:125], v[0:1], v[172:173], 0 op_sel_hi:[1,1,0]
	global_store_dwordx4 v[158:159], v[120:123], off nt
	global_store_dwordx4 v[158:159], v[124:127], off offset:16 nt
	ds_read_b32 v120, v169 offset:4160
	s_nop 0
	v_add_u32_e32 v124, 16, v146
	v_ashrrev_i32_e32 v125, 31, v124
	s_waitcnt lgkmcnt(0)
	v_pk_mul_f32 v[104:105], v[104:105], v[120:121] op_sel_hi:[1,0]
	v_pk_mul_f32 v[110:111], v[110:111], v[120:121] op_sel_hi:[1,0]
	v_pk_mul_f32 v[108:109], v[108:109], v[120:121] op_sel_hi:[1,0]
	v_pk_mul_f32 v[106:107], v[106:107], v[120:121] op_sel_hi:[1,0]
	v_pk_fma_f32 v[120:121], v[0:1], v[104:105], 0 op_sel_hi:[1,1,0]
	v_lshlrev_b64 v[104:105], 12, v[124:125]
	v_lshl_add_u64 v[104:105], v[174:175], 0, v[104:105]
	v_pk_fma_f32 v[110:111], v[6:7], v[110:111], 0 op_sel_hi:[1,1,0]
	v_pk_fma_f32 v[108:109], v[4:5], v[108:109], 0 op_sel_hi:[1,1,0]
	v_lshl_add_u64 v[104:105], v[104:105], 0, v[144:145]
	v_pk_fma_f32 v[122:123], v[2:3], v[106:107], 0 op_sel_hi:[1,1,0]
	global_store_dwordx4 v[104:105], v[108:111], off nt
	global_store_dwordx4 v[104:105], v[120:123], off offset:16 nt
	ds_read_b32 v106, v169 offset:4224
	v_add_u32_e32 v110, 32, v146
	v_ashrrev_i32_e32 v111, 31, v110
	s_waitcnt lgkmcnt(0)
	v_pk_mul_f32 v[88:89], v[88:89], v[106:107] op_sel_hi:[1,0]
	v_pk_mul_f32 v[94:95], v[94:95], v[106:107] op_sel_hi:[1,0]
	v_pk_mul_f32 v[92:93], v[92:93], v[106:107] op_sel_hi:[1,0]
	v_pk_mul_f32 v[90:91], v[90:91], v[106:107] op_sel_hi:[1,0]
	v_pk_fma_f32 v[106:107], v[0:1], v[88:89], 0 op_sel_hi:[1,1,0]
	v_lshlrev_b64 v[88:89], 12, v[110:111]
	v_lshl_add_u64 v[88:89], v[174:175], 0, v[88:89]
	v_pk_fma_f32 v[94:95], v[6:7], v[94:95], 0 op_sel_hi:[1,1,0]
	v_pk_fma_f32 v[92:93], v[4:5], v[92:93], 0 op_sel_hi:[1,1,0]
	v_lshl_add_u64 v[88:89], v[88:89], 0, v[144:145]
	v_pk_fma_f32 v[108:109], v[2:3], v[90:91], 0 op_sel_hi:[1,1,0]
	global_store_dwordx4 v[88:89], v[92:95], off nt
	global_store_dwordx4 v[88:89], v[106:109], off offset:16 nt
	ds_read_b32 v90, v169 offset:4288
	v_add_u32_e32 v94, 48, v146
	v_ashrrev_i32_e32 v95, 31, v94
	s_waitcnt lgkmcnt(0)
	v_pk_mul_f32 v[72:73], v[72:73], v[90:91] op_sel_hi:[1,0]
	v_pk_mul_f32 v[78:79], v[78:79], v[90:91] op_sel_hi:[1,0]
	v_pk_mul_f32 v[76:77], v[76:77], v[90:91] op_sel_hi:[1,0]
	v_pk_mul_f32 v[74:75], v[74:75], v[90:91] op_sel_hi:[1,0]
	v_pk_fma_f32 v[90:91], v[0:1], v[72:73], 0 op_sel_hi:[1,1,0]
	v_lshlrev_b64 v[72:73], 12, v[94:95]
	v_lshl_add_u64 v[72:73], v[174:175], 0, v[72:73]
	v_pk_fma_f32 v[78:79], v[6:7], v[78:79], 0 op_sel_hi:[1,1,0]
	v_pk_fma_f32 v[76:77], v[4:5], v[76:77], 0 op_sel_hi:[1,1,0]
	v_lshl_add_u64 v[72:73], v[72:73], 0, v[144:145]
	v_pk_fma_f32 v[92:93], v[2:3], v[74:75], 0 op_sel_hi:[1,1,0]
	global_store_dwordx4 v[72:73], v[76:79], off nt
	global_store_dwordx4 v[72:73], v[90:93], off offset:16 nt
	ds_read_b32 v74, v169 offset:4608
	s_waitcnt lgkmcnt(0)
	v_pk_mul_f32 v[62:63], v[62:63], v[74:75] op_sel_hi:[1,0]
	v_pk_mul_f32 v[60:61], v[60:61], v[74:75] op_sel_hi:[1,0]
	v_pk_mul_f32 v[76:77], v[58:59], v[74:75] op_sel_hi:[1,0]
	v_pk_mul_f32 v[74:75], v[56:57], v[74:75] op_sel_hi:[1,0]
	v_pk_fma_f32 v[56:57], v[4:5], v[60:61], 0 op_sel_hi:[1,1,0]
	v_pk_fma_f32 v[60:61], v[0:1], v[74:75], 0 op_sel_hi:[1,1,0]
	v_lshlrev_b64 v[74:75], 12, v[170:171]
	v_lshl_add_u64 v[74:75], v[174:175], 0, v[74:75]
	v_pk_fma_f32 v[58:59], v[6:7], v[62:63], 0 op_sel_hi:[1,1,0]
	v_lshl_add_u64 v[74:75], v[74:75], 0, v[144:145]
	v_pk_fma_f32 v[62:63], v[2:3], v[76:77], 0 op_sel_hi:[1,1,0]
	global_store_dwordx4 v[74:75], v[56:59], off nt
	global_store_dwordx4 v[74:75], v[60:63], off offset:16 nt
	ds_read_b32 v56, v169 offset:4672
	v_add_u32_e32 v58, 0x90, v146
	v_ashrrev_i32_e32 v59, 31, v58
	s_waitcnt lgkmcnt(0)
	v_pk_mul_f32 v[46:47], v[46:47], v[56:57] op_sel_hi:[1,0]
	v_pk_mul_f32 v[44:45], v[44:45], v[56:57] op_sel_hi:[1,0]
	v_pk_mul_f32 v[42:43], v[42:43], v[56:57] op_sel_hi:[1,0]
	v_pk_mul_f32 v[40:41], v[40:41], v[56:57] op_sel_hi:[1,0]
	v_lshlrev_b64 v[56:57], 12, v[58:59]
	v_lshl_add_u64 v[56:57], v[174:175], 0, v[56:57]
	v_pk_fma_f32 v[46:47], v[6:7], v[46:47], 0 op_sel_hi:[1,1,0]
	v_pk_fma_f32 v[44:45], v[4:5], v[44:45], 0 op_sel_hi:[1,1,0]
	v_lshl_add_u64 v[56:57], v[56:57], 0, v[144:145]
	v_pk_fma_f32 v[42:43], v[2:3], v[42:43], 0 op_sel_hi:[1,1,0]
	v_pk_fma_f32 v[40:41], v[0:1], v[40:41], 0 op_sel_hi:[1,1,0]
	global_store_dwordx4 v[56:57], v[44:47], off nt
	global_store_dwordx4 v[56:57], v[40:43], off offset:16 nt
	ds_read_b32 v40, v169 offset:4736
	s_nop 0
	v_add_u32_e32 v42, 0xa0, v146
	v_ashrrev_i32_e32 v43, 31, v42
	s_waitcnt lgkmcnt(0)
;     __device__ __forceinline__ void operator()(AccT& acc, const pg8::Unit& u, int wr, int wc, int fr_, int fq_) const {
;     ...
;         const float* sh = MODE == 0 ? shift + (size_t)bidx * NADA : nullptr;
; #pragma unroll
;         for (int bj = 0; bj < 2; ++bj) { const int col = u.pn * 256 + bj * 128 + wc * 32 + 8 * fq;
;             const f32x4 g0 = *(const f32x4*)(gvec + col), g1 = *(const f32x4*)(gvec + col + 4);
;             f32x4 a0 = g0, a1 = g1, b0 = {0.f, 0.f, 0.f, 0.f}, b1 = b0;
;             if (MODE == 0) { a0 = g0 * (*(const f32x4*)(sh + D + col) + 1.f); a1 = g1 * (*(const f32x4*)(sh + D + col + 4) + 1.f); b0 = *(const f32x4*)(sh + col); b1 = *(const f32x4*)(sh + col + 4); }
; #pragma unroll
;             for (int ai = 0; ai < 2; ++ai)
; #pragma unroll
;                 for (int m = 0; m < 4; ++m) { const int rl = ai * 128 + wr * 64 + m * 16 + fr; const size_t row = (size_t)u.pm * 256 + rl; const float rstd = sred[1024 + rl];
;                     const f32x4 y0 = acc[ai][bj][m][0] * rstd * a0 + b0, y1 = acc[ai][bj][m][1] * rstd * a1 + b1;
;                     if (MODE == 0) *(bf16x8*)(Hout + row * D + col) = pack8(y0[0], y0[1], y0[2], y0[3], y1[0], y1[1], y1[2], y1[3]);
;                     else { __builtin_nontemporal_store(y0, (f32x4*)(X + row * D + col)); __builtin_nontemporal_store(y1, (f32x4*)(X + row * D + col + 4)); }
;                     __builtin_amdgcn_sched_barrier(0); }
	v_pk_mul_f32 v[30:31], v[30:31], v[40:41] op_sel_hi:[1,0]
	v_pk_mul_f32 v[28:29], v[28:29], v[40:41] op_sel_hi:[1,0]
	v_pk_mul_f32 v[26:27], v[26:27], v[40:41] op_sel_hi:[1,0]
	v_pk_mul_f32 v[24:25], v[24:25], v[40:41] op_sel_hi:[1,0]
	v_lshlrev_b64 v[40:41], 12, v[42:43]
	v_lshl_add_u64 v[40:41], v[174:175], 0, v[40:41]
	v_pk_fma_f32 v[30:31], v[6:7], v[30:31], 0 op_sel_hi:[1,1,0]
	v_pk_fma_f32 v[28:29], v[4:5], v[28:29], 0 op_sel_hi:[1,1,0]
	v_lshl_add_u64 v[40:41], v[40:41], 0, v[144:145]
	v_pk_fma_f32 v[26:27], v[2:3], v[26:27], 0 op_sel_hi:[1,1,0]
	v_pk_fma_f32 v[24:25], v[0:1], v[24:25], 0 op_sel_hi:[1,1,0]
	global_store_dwordx4 v[40:41], v[28:31], off nt
	global_store_dwordx4 v[40:41], v[24:27], off offset:16 nt
	ds_read_b32 v24, v169 offset:4800
	s_nop 0
	v_add_u32_e32 v26, 0xb0, v146
	v_ashrrev_i32_e32 v27, 31, v26
	s_waitcnt lgkmcnt(0)
	v_pk_mul_f32 v[28:29], v[152:153], v[24:25] op_sel_hi:[1,0]
	v_pk_mul_f32 v[30:31], v[154:155], v[24:25] op_sel_hi:[1,0]
	v_pk_fma_f32 v[6:7], v[6:7], v[28:29], 0 op_sel_hi:[1,1,0]
	v_pk_mul_f32 v[28:29], v[148:149], v[24:25] op_sel_hi:[1,0]
	v_pk_mul_f32 v[24:25], v[150:151], v[24:25] op_sel_hi:[1,0]
	v_pk_fma_f32 v[4:5], v[4:5], v[30:31], 0 op_sel_hi:[1,1,0]
	v_pk_fma_f32 v[0:1], v[0:1], v[24:25], 0 op_sel_hi:[1,1,0]
	v_lshlrev_b64 v[24:25], 12, v[26:27]
	v_lshl_add_u64 v[24:25], v[174:175], 0, v[24:25]
	v_lshl_add_u64 v[42:43], v[24:25], 0, v[144:145]
	v_pk_fma_f32 v[2:3], v[2:3], v[28:29], 0 op_sel_hi:[1,1,0]
	global_store_dwordx4 v[42:43], v[4:7], off nt
	global_store_dwordx4 v[42:43], v[0:3], off offset:16 nt
	s_nop 0
	ds_read_b32 v24, v169 offset:4096
	s_waitcnt lgkmcnt(0)
	v_pk_mul_f32 v[26:27], v[118:119], v[24:25] op_sel_hi:[1,0]
	v_pk_mul_f32 v[28:29], v[116:117], v[24:25] op_sel_hi:[1,0]
	v_pk_mul_f32 v[30:31], v[114:115], v[24:25] op_sel_hi:[1,0]
	v_pk_mul_f32 v[44:45], v[112:113], v[24:25] op_sel_hi:[1,0]
	s_waitcnt vmcnt(16)
	v_pk_fma_f32 v[26:27], v[198:199], v[26:27], 0 op_sel_hi:[1,1,0]
	v_pk_fma_f32 v[24:25], v[196:197], v[28:29], 0 op_sel_hi:[1,1,0]
	v_pk_fma_f32 v[30:31], v[202:203], v[30:31], 0 op_sel_hi:[1,1,0]
	v_pk_fma_f32 v[28:29], v[200:201], v[44:45], 0 op_sel_hi:[1,1,0]
	global_store_dwordx4 v[158:159], v[24:27], off offset:512 nt
	global_store_dwordx4 v[158:159], v[28:31], off offset:528 nt
	ds_read_b32 v24, v169 offset:4160
	s_waitcnt lgkmcnt(0)
	v_pk_mul_f32 v[26:27], v[102:103], v[24:25] op_sel_hi:[1,0]
	v_pk_mul_f32 v[28:29], v[100:101], v[24:25] op_sel_hi:[1,0]
	v_pk_mul_f32 v[30:31], v[98:99], v[24:25] op_sel_hi:[1,0]
	v_pk_mul_f32 v[44:45], v[96:97], v[24:25] op_sel_hi:[1,0]
	v_pk_fma_f32 v[26:27], v[198:199], v[26:27], 0 op_sel_hi:[1,1,0]
	v_pk_fma_f32 v[24:25], v[196:197], v[28:29], 0 op_sel_hi:[1,1,0]
	v_pk_fma_f32 v[30:31], v[202:203], v[30:31], 0 op_sel_hi:[1,1,0]
	v_pk_fma_f32 v[28:29], v[200:201], v[44:45], 0 op_sel_hi:[1,1,0]
	global_store_dwordx4 v[104:105], v[24:27], off offset:512 nt
	global_store_dwordx4 v[104:105], v[28:31], off offset:528 nt
	ds_read_b32 v24, v169 offset:4224
	s_waitcnt lgkmcnt(0)
	v_pk_mul_f32 v[26:27], v[86:87], v[24:25] op_sel_hi:[1,0]
	v_pk_mul_f32 v[28:29], v[84:85], v[24:25] op_sel_hi:[1,0]
	v_pk_mul_f32 v[30:31], v[82:83], v[24:25] op_sel_hi:[1,0]
	v_pk_mul_f32 v[44:45], v[80:81], v[24:25] op_sel_hi:[1,0]
	v_pk_fma_f32 v[26:27], v[198:199], v[26:27], 0 op_sel_hi:[1,1,0]
	v_pk_fma_f32 v[24:25], v[196:197], v[28:29], 0 op_sel_hi:[1,1,0]
	v_pk_fma_f32 v[30:31], v[202:203], v[30:31], 0 op_sel_hi:[1,1,0]
	v_pk_fma_f32 v[28:29], v[200:201], v[44:45], 0 op_sel_hi:[1,1,0]
	global_store_dwordx4 v[88:89], v[24:27], off offset:512 nt
	global_store_dwordx4 v[88:89], v[28:31], off offset:528 nt
	ds_read_b32 v24, v169 offset:4288
	s_waitcnt lgkmcnt(0)
;     __device__ __forceinline__ void operator()(AccT& acc, const pg8::Unit& u, int wr, int wc, int fr_, int fq_) const {
;     ...
; #pragma unroll
;             for (int ai = 0; ai < 2; ++ai)
; #pragma unroll
;                 for (int m = 0; m < 4; ++m) { const int rl = ai * 128 + wr * 64 + m * 16 + fr; const size_t row = (size_t)u.pm * 256 + rl; const float rstd = sred[1024 + rl];
;                     const f32x4 y0 = acc[ai][bj][m][0] * rstd * a0 + b0, y1 = acc[ai][bj][m][1] * rstd * a1 + b1;
;                     if (MODE == 0) *(bf16x8*)(Hout + row * D + col) = pack8(y0[0], y0[1], y0[2], y0[3], y1[0], y1[1], y1[2], y1[3]);
;                     else { __builtin_nontemporal_store(y0, (f32x4*)(X + row * D + col)); __builtin_nontemporal_store(y1, (f32x4*)(X + row * D + col + 4)); }
;                     __builtin_amdgcn_sched_barrier(0); }
;         }
;         __syncthreads();
	v_pk_mul_f32 v[26:27], v[70:71], v[24:25] op_sel_hi:[1,0]
	v_pk_mul_f32 v[28:29], v[68:69], v[24:25] op_sel_hi:[1,0]
	v_pk_mul_f32 v[30:31], v[66:67], v[24:25] op_sel_hi:[1,0]
	v_pk_mul_f32 v[44:45], v[64:65], v[24:25] op_sel_hi:[1,0]
	v_pk_fma_f32 v[26:27], v[198:199], v[26:27], 0 op_sel_hi:[1,1,0]
	v_pk_fma_f32 v[24:25], v[196:197], v[28:29], 0 op_sel_hi:[1,1,0]
	v_pk_fma_f32 v[30:31], v[202:203], v[30:31], 0 op_sel_hi:[1,1,0]
	v_pk_fma_f32 v[28:29], v[200:201], v[44:45], 0 op_sel_hi:[1,1,0]
	global_store_dwordx4 v[72:73], v[24:27], off offset:512 nt
	global_store_dwordx4 v[72:73], v[28:31], off offset:528 nt
	ds_read_b32 v24, v169 offset:4608
	s_waitcnt lgkmcnt(0)
	v_pk_mul_f32 v[26:27], v[54:55], v[24:25] op_sel_hi:[1,0]
	v_pk_mul_f32 v[28:29], v[52:53], v[24:25] op_sel_hi:[1,0]
	v_pk_mul_f32 v[30:31], v[50:51], v[24:25] op_sel_hi:[1,0]
	v_pk_mul_f32 v[44:45], v[48:49], v[24:25] op_sel_hi:[1,0]
	v_pk_fma_f32 v[26:27], v[198:199], v[26:27], 0 op_sel_hi:[1,1,0]
	v_pk_fma_f32 v[24:25], v[196:197], v[28:29], 0 op_sel_hi:[1,1,0]
	v_pk_fma_f32 v[30:31], v[202:203], v[30:31], 0 op_sel_hi:[1,1,0]
	v_pk_fma_f32 v[28:29], v[200:201], v[44:45], 0 op_sel_hi:[1,1,0]
	global_store_dwordx4 v[74:75], v[24:27], off offset:512 nt
	global_store_dwordx4 v[74:75], v[28:31], off offset:528 nt
	ds_read_b32 v24, v169 offset:4672
	s_waitcnt lgkmcnt(0)
	v_pk_mul_f32 v[26:27], v[38:39], v[24:25] op_sel_hi:[1,0]
	v_pk_mul_f32 v[28:29], v[36:37], v[24:25] op_sel_hi:[1,0]
	v_pk_mul_f32 v[30:31], v[34:35], v[24:25] op_sel_hi:[1,0]
	v_pk_mul_f32 v[32:33], v[32:33], v[24:25] op_sel_hi:[1,0]
	v_pk_fma_f32 v[26:27], v[198:199], v[26:27], 0 op_sel_hi:[1,1,0]
	v_pk_fma_f32 v[24:25], v[196:197], v[28:29], 0 op_sel_hi:[1,1,0]
	v_pk_fma_f32 v[30:31], v[202:203], v[30:31], 0 op_sel_hi:[1,1,0]
	v_pk_fma_f32 v[28:29], v[200:201], v[32:33], 0 op_sel_hi:[1,1,0]
	global_store_dwordx4 v[56:57], v[24:27], off offset:512 nt
	global_store_dwordx4 v[56:57], v[28:31], off offset:528 nt
	ds_read_b32 v24, v169 offset:4736
	s_waitcnt lgkmcnt(0)
	v_pk_mul_f32 v[22:23], v[22:23], v[24:25] op_sel_hi:[1,0]
	v_pk_mul_f32 v[20:21], v[20:21], v[24:25] op_sel_hi:[1,0]
	v_pk_mul_f32 v[26:27], v[18:19], v[24:25] op_sel_hi:[1,0]
	v_pk_mul_f32 v[24:25], v[16:17], v[24:25] op_sel_hi:[1,0]
	v_pk_fma_f32 v[18:19], v[198:199], v[22:23], 0 op_sel_hi:[1,1,0]
	v_pk_fma_f32 v[16:17], v[196:197], v[20:21], 0 op_sel_hi:[1,1,0]
	v_pk_fma_f32 v[22:23], v[202:203], v[26:27], 0 op_sel_hi:[1,1,0]
	v_pk_fma_f32 v[20:21], v[200:201], v[24:25], 0 op_sel_hi:[1,1,0]
	global_store_dwordx4 v[40:41], v[16:19], off offset:512 nt
	global_store_dwordx4 v[40:41], v[20:23], off offset:528 nt
	ds_read_b32 v16, v169 offset:4800
	s_waitcnt lgkmcnt(0)
	v_pk_mul_f32 v[12:13], v[12:13], v[16:17] op_sel_hi:[1,0]
	v_pk_mul_f32 v[14:15], v[14:15], v[16:17] op_sel_hi:[1,0]
	v_pk_mul_f32 v[8:9], v[8:9], v[16:17] op_sel_hi:[1,0]
	v_pk_mul_f32 v[10:11], v[10:11], v[16:17] op_sel_hi:[1,0]
	v_pk_fma_f32 v[2:3], v[198:199], v[12:13], 0 op_sel_hi:[1,1,0]
	v_pk_fma_f32 v[0:1], v[196:197], v[14:15], 0 op_sel_hi:[1,1,0]
	v_pk_fma_f32 v[6:7], v[202:203], v[8:9], 0 op_sel_hi:[1,1,0]
	v_pk_fma_f32 v[4:5], v[200:201], v[10:11], 0 op_sel_hi:[1,1,0]
	global_store_dwordx4 v[42:43], v[0:3], off offset:512 nt
	global_store_dwordx4 v[42:43], v[4:7], off offset:528 nt
	s_and_b64 vcc, exec, s[6:7]
	s_mov_b64 s[4:5], -1
	s_barrier
	s_cbranch_vccnz .LBB0_2311
	s_andn2_b64 vcc, exec, s[18:19]
	s_cbranch_vccnz .LBB0_2310
	s_barrier
	s_branch .LBB0_2310
